# attention LDS-DMA issue: dropped m0 save/restore (m0 is never read elsewhere)
# baseline (speedup 1.0000x reference)
; __device__ __forceinline__ int fresh_tid() { int t = (int)threadIdx.x; asm volatile("" : "+v"(t)); return t; }
; #define WAIT_BAR(N) asm volatile("s_waitcnt vmcnt(" #N ") lgkmcnt(0)\n\ts_barrier":::"memory")
;   #define DMA_K(t,slot) glds16(ksrc+(long)(t)*KVBLK*KVP,(unsigned)__builtin_amdgcn_readfirstlane(kdst+(slot)))
;   #define DMA_V(t,slot) glds16(vsrc+(long)(t)*KVBLK*KVP,(unsigned)__builtin_amdgcn_readfirstlane(vdst+(slot)))
;   #define CMASK(P0,P1,t) do{}while(0)
;   #define CMASK(P0,P1,t) do{}while(0)
;   #define CMASK(P0,P1,t) do{}while(0)
; template<int THRL> __device__ __forceinline__ void attn_unit(int b,int h,int qb,const bf16*Q,const bf16*__restrict__ K,const bf16*__restrict__ V,bf16*O,char*shm){
;   const int tid=fresh_tid(),lane=tid&63,r32=lane&31,hi=lane>>5; const int wid=__builtin_amdgcn_readfirstlane(tid>>6);
;   const long rowbase=(long)b*SEQ; const int q0=qb*QB;
;   const bf16*Qw=Q+(rowbase+q0+wid*QBLK)*QP+h*D;
;   const int kvh=h/(NHEAD/NKVH); const bf16*Kh=K+rowbase*KVP+kvh*D,*Vh=V+rowbase*KVP+kvh*D;
;   const unsigned lds0=(unsigned)(uintptr_t)shm;
;   float*wsf=(float*)(shm+LDS_WS)+wid*64;
;   const bf16*ksrc=Kh+(long)lane*KVP+wid*8;
;   const bf16*vsrc=Vh+(long)(16*(wid&3)+(lane>>2))*KVP+(wid>>2)*32+(lane&3)*8;
;   const unsigned kdst=lds0+LDS_K+wid*1024, vdst=lds0+LDS_V+wid*1024;
;     ...
;   const int vb0=(int)(lds0+LDS_V)+((lane>>4)&1)*32+(lane&3)*8+(4*hi+((lane&15)>>2))*64;
;   const char*Kbase=shm+LDS_K; bf16x8 kf[8];
;   const lds_cptr shm3=(lds_cptr)shm; const lds_cptr kp0=shm3+LDS_K+hi*1024+r32*16; const lds_cptr vp0=shm3+LDS_V+((lane>>4)&1)*32+(lane&3)*8+(4*hi+((lane&15)>>2))*64;
;   constexpr int NT=SEQ/KVBLK;
;   DMA_K(0,0);DMA_V(0,0);DMA_K(1,SLOTB);
;   bf16x8 qr[4];
;   #pragma unroll
;   for(int d0=0;d0<4;++d0)qr[d0]=*reinterpret_cast<const bf16x8*>(&Qw[(long)r32*QP+d0*16+hi*8]);
;   float mhat=0.f,l_reg=0.f;f32x16 o[2];o[0]=f32x16{};o[1]=f32x16{};f32x16 negm=f32x16{};asm volatile("":"+v"(negm));
;   const int qrel=wid*QBLK+r32;
;     ...
;   bool resc=false;
;     ...
;   f32x16 pA0,pA1,pB0,pB1;
;   int sl_prev=0,sl_cur=0,sl_next=SLOTB;
;     ...
;   DMA_K(2,2*SLOTB);
;   WAIT_BAR(3);
;   qkt(pA0,pA1,Kbase,qr,negm,r32,hi);asm volatile("s_nop 15\n\ts_nop 7":"+v"(pA0),"+v"(pA1));CMASK(pA0,pA1,0);
;   START(pA0,pA1);
;   _Pragma("unroll") for(int r=0;r<16;++r)pA1[r]=__builtin_amdgcn_exp2f(pA1[r]);
;   WAIT_BAR(0);
.LBB0_777:
	s_ashr_i32 s3, s96, 31
	s_lshr_b32 s3, s3, 28
	s_add_i32 s3, s96, s3
	s_ashr_i32 s6, s3, 4
	s_and_b32 s3, s3, 0xfffff0
	s_sub_i32 s3, s96, s3
	v_mov_b32_e32 v82, v228
	s_lshl_b32 s3, s3, 8
	v_readfirstlane_b32 s50, v82
	s_add_i32 s13, s6, s77
	s_ashr_i32 s97, s50, 6
	s_ashr_i32 s6, s3, 31
	s_add_u32 s3, s8, s3
	s_addc_u32 s6, s9, s6
	s_lshl_b32 s7, s97, 5
	s_ashr_i32 s18, s7, 31
	s_add_u32 s40, s3, s7
	s_addc_u32 s41, s6, s18
	s_mul_i32 s3, s41, 0xc00
	s_mul_hi_u32 s6, s40, 0xc00
	s_add_i32 s6, s6, s3
	s_mul_i32 s3, s40, 0xc00
	s_add_u32 s3, s4, s3
	s_addc_u32 s22, s5, s6
	s_lshl_b32 s6, s13, 6
	s_ashr_i32 s7, s6, 31
	s_lshl_b64 s[18:19], s[6:7], 1
	s_add_u32 s6, s3, s18
	s_addc_u32 s7, s22, s19
	s_ashr_i32 s3, s13, 31
	s_lshr_b32 s3, s3, 30
	s_add_i32 s13, s13, s3
	s_lshl_b32 s3, s13, 4
	s_and_b32 s22, s3, 0xffffffc0
	s_ashr_i32 s23, s22, 31
	s_lshl_b64 s[42:43], s[22:23], 1
	v_and_b32_e32 v196, 63, v82
	s_add_u32 s22, s92, s42
	s_addc_u32 s23, s93, s43
	v_mul_u32_u24_e32 v0, 0x600, v196
	s_add_u32 s38, s94, s42
	v_lshlrev_b32_e32 v180, 1, v0
	s_addc_u32 s39, s95, s43
	v_lshl_add_u64 v[0:1], s[22:23], 0, v[180:181]
	s_lshl_b32 s22, s97, 3
	s_ashr_i32 s23, s22, 31
	s_lshl_b64 s[44:45], s[22:23], 1
	v_lshl_add_u64 v[186:187], v[0:1], 0, s[44:45]
	s_lshl_b32 s3, s97, 4
	v_bfe_u32 v0, v82, 2, 4
	v_and_or_b32 v0, s3, 48, v0
	s_ashr_i32 s3, s50, 3
	s_and_b32 s22, s3, 0xffffffe0
	s_ashr_i32 s23, s22, 31
	s_and_b32 s13, s50, 0x3fffffc0
	v_mul_u32_u24_e32 v0, 0x600, v0
	s_lshl_b64 s[50:51], s[22:23], 1
	s_lshl_b32 s3, s97, 10
	v_lshlrev_b32_e32 v80, 1, v0
	v_mov_b32_e32 v81, v181
	v_lshlrev_b32_e32 v197, 3, v82
	s_cmp_lg_u32 0, -1
	v_lshl_add_u64 v[0:1], s[38:39], 0, v[80:81]
	v_and_b32_e32 v200, 24, v197
	s_cselect_b32 s22, 0, 0
	v_lshl_add_u64 v[0:1], v[0:1], 0, s[50:51]
	v_lshlrev_b32_e32 v2, 1, v200
	v_mov_b32_e32 v3, v181
	s_add_i32 s38, s3, s22
	s_mov_b32 m0, s38
	s_nop 0
	global_load_lds_dwordx4 v[186:187], off
	v_and_b32_e32 v198, 31, v82
	v_bfe_u32 v199, v82, 5, 1
	v_lshl_add_u64 v[188:189], v[0:1], 0, v[2:3]
	s_add_i32 s39, s38, 0x6000
	s_mov_b32 m0, s39
	s_nop 0
	global_load_lds_dwordx4 v[188:189], off
	v_lshl_add_u64 v[0:1], v[186:187], 0, s[82:83]
	s_add_i32 s3, s38, 0x2000
	s_mov_b32 m0, s3
	s_nop 0
	global_load_lds_dwordx4 v[0:1], off
	v_mul_u32_u24_e32 v0, 0x600, v198
	v_lshlrev_b32_e32 v203, 4, v199
	v_lshl_or_b32 v8, v0, 1, v203
	global_load_dwordx4 v[140:143], v8, s[6:7]
	global_load_dwordx4 v[136:139], v8, s[6:7] offset:32
	global_load_dwordx4 v[128:131], v8, s[6:7] offset:64
	global_load_dwordx4 v[120:123], v8, s[6:7] offset:96
	v_mov_b32_e32 v0, v181
	v_mov_b32_e32 v1, v181
	v_mov_b32_e32 v2, v181
	v_mov_b32_e32 v4, v181
	v_mov_b32_e32 v5, v181
	v_mov_b32_e32 v6, v181
	v_mov_b32_e32 v7, v181
	v_mov_b32_e32 v8, v181
	v_mov_b32_e32 v9, v181
	v_mov_b32_e32 v10, v181
	v_mov_b32_e32 v11, v181
	v_mov_b32_e32 v12, v181
	v_mov_b32_e32 v13, v181
	v_mov_b32_e32 v14, v181
	v_mov_b32_e32 v15, v181
	v_lshlrev_b32_e32 v16, 10, v199
	v_lshlrev_b32_e32 v17, 4, v198
	v_add3_u32 v208, 0, v16, v17
	v_lshl_add_u64 v[16:17], v[186:187], 0, s[84:85]
	s_add_i32 s3, s38, 0x4000
	s_mov_b32 m0, s3
	s_nop 0
	global_load_lds_dwordx4 v[16:17], off
	s_waitcnt vmcnt(3) lgkmcnt(0)
	s_barrier
	ds_read_b128 v[32:35], v208
	ds_read_b128 v[36:39], v208 offset:512
	s_lshl_b32 s6, s13, 2
	s_add_i32 s13, s6, 0
	s_mov_b32 s52, -1
	s_mov_b32 s22, 0
	s_movk_i32 s3, 0x2000
	s_movk_i32 s53, 0x4000
	v_lshl_add_u32 v204, v198, 2, s13
	s_waitcnt vmcnt(3) lgkmcnt(1)
	v_mfma_f32_32x32x16_bf16 v[16:31], v[32:35], v[140:143], v[0:15]
	s_waitcnt lgkmcnt(0)
	v_mfma_f32_32x32x16_bf16 v[0:15], v[36:39], v[140:143], v[0:15]
	ds_read_b128 v[32:35], v208 offset:2048
	ds_read_b128 v[36:39], v208 offset:2560
	s_waitcnt vmcnt(2) lgkmcnt(1)
	v_mfma_f32_32x32x16_bf16 v[16:31], v[32:35], v[136:139], v[16:31]
	s_waitcnt lgkmcnt(0)
	v_mfma_f32_32x32x16_bf16 v[0:15], v[36:39], v[136:139], v[0:15]
	ds_read_b128 v[32:35], v208 offset:4096
	ds_read_b128 v[36:39], v208 offset:4608
	s_waitcnt vmcnt(1) lgkmcnt(1)
	v_mfma_f32_32x32x16_bf16 v[16:31], v[32:35], v[128:131], v[16:31]
	ds_read_b128 v[32:35], v208 offset:6144
	s_waitcnt lgkmcnt(1)
	v_mfma_f32_32x32x16_bf16 v[0:15], v[36:39], v[128:131], v[0:15]
	ds_read_b128 v[36:39], v208 offset:6656
	s_waitcnt vmcnt(0) lgkmcnt(1)
	v_mfma_f32_32x32x16_bf16 v[16:31], v[32:35], v[120:123], v[16:31]
	v_lshlrev_b32_e32 v32, 1, v82
	v_lshlrev_b32_e32 v33, 4, v82
	v_and_b32_e32 v201, 32, v32
	v_and_b32_e32 v32, 0xc0, v33
	v_lshl_or_b32 v202, v199, 8, v32
	v_add_u32_e32 v83, 0, v201
	v_add3_u32 v209, v83, v200, v202
	s_waitcnt lgkmcnt(0)
	v_mfma_f32_32x32x16_bf16 v[0:15], v[36:39], v[120:123], v[0:15]
	s_nop 15
	s_nop 7
	s_nop 0
	v_max3_f32 v32, v16, v17, v0
	v_max3_f32 v33, v18, v19, v1
	s_nop 0
	v_max3_f32 v32, v32, v2, v3
	v_max3_f32 v33, v33, v22, v23
	s_nop 0
	v_max3_f32 v32, v32, v20, v21
	v_max3_f32 v33, v33, v6, v7
	s_nop 0
	v_max3_f32 v32, v32, v4, v5
	v_max3_f32 v33, v33, v26, v27
	s_nop 0
	v_max3_f32 v32, v32, v24, v25
	v_max3_f32 v33, v33, v10, v11
	s_nop 0
	v_max3_f32 v32, v32, v8, v9
	v_max3_f32 v33, v33, v30, v31
	s_nop 0
	v_max3_f32 v32, v32, v28, v29
	v_max3_f32 v33, v33, v14, v15
	s_nop 0
	v_max3_f32 v32, v32, v12, v13
	s_nop 0
	v_max_f32_e32 v32, v32, v33
	s_nop 0
	v_mov_b32_e32 v33, v32
	s_nop 1
	v_permlane32_swap_b32_e32 v32, v33
	v_max_f32_e32 v32, v32, v33
	s_nop 0
	v_add_f32_e32 v206, v181, v32
	v_sub_f32_e32 v16, v16, v32
	v_sub_f32_e32 v0, v0, v32
	v_sub_f32_e32 v17, v17, v32
	v_sub_f32_e32 v1, v1, v32
	v_sub_f32_e32 v18, v18, v32
	v_sub_f32_e32 v2, v2, v32
	v_sub_f32_e32 v19, v19, v32
	v_sub_f32_e32 v3, v3, v32
	v_sub_f32_e32 v20, v20, v32
	v_sub_f32_e32 v4, v4, v32
	v_sub_f32_e32 v21, v21, v32
	v_sub_f32_e32 v5, v5, v32
	v_sub_f32_e32 v22, v22, v32
	v_sub_f32_e32 v6, v6, v32
	v_sub_f32_e32 v23, v23, v32
	v_sub_f32_e32 v7, v7, v32
	v_sub_f32_e32 v24, v24, v32
	v_sub_f32_e32 v8, v8, v32
	v_sub_f32_e32 v25, v25, v32
	v_sub_f32_e32 v9, v9, v32
	v_sub_f32_e32 v26, v26, v32
	v_sub_f32_e32 v10, v10, v32
	v_sub_f32_e32 v27, v27, v32
	v_sub_f32_e32 v11, v11, v32
	v_sub_f32_e32 v28, v28, v32
	v_sub_f32_e32 v12, v12, v32
	v_sub_f32_e32 v29, v29, v32
	v_sub_f32_e32 v13, v13, v32
	v_sub_f32_e32 v30, v30, v32
	v_sub_f32_e32 v14, v14, v32
	v_sub_f32_e32 v31, v31, v32
	v_sub_f32_e32 v15, v15, v32
	s_nop 0
	v_xor_b32_e32 v32, 0x80000000, v206
	v_mov_b32_e32 v33, v32
	v_mov_b32_e32 v34, v32
	v_mov_b32_e32 v35, v32
	v_mov_b32_e32 v36, v32
	v_mov_b32_e32 v37, v32
	v_mov_b32_e32 v38, v32
	v_mov_b32_e32 v39, v32
	v_mov_b32_e32 v40, v32
	v_mov_b32_e32 v41, v32
	v_mov_b32_e32 v42, v32
	v_mov_b32_e32 v43, v32
	v_mov_b32_e32 v44, v32
	v_mov_b32_e32 v45, v32
	v_mov_b32_e32 v46, v32
	v_mov_b32_e32 v47, v32
	s_waitcnt vmcnt(0) lgkmcnt(0)
	s_barrier
; #define WAIT_BAR(N) asm volatile("s_waitcnt vmcnt(" #N ") lgkmcnt(0)\n\ts_barrier":::"memory")
;   #define DMA_K(t,slot) glds16(ksrc+(long)(t)*KVBLK*KVP,(unsigned)__builtin_amdgcn_readfirstlane(kdst+(slot)))
;   #define DMA_V(t,slot) glds16(vsrc+(long)(t)*KVBLK*KVP,(unsigned)__builtin_amdgcn_readfirstlane(vdst+(slot)))
;   #define ROT() do{sl_prev=sl_cur;sl_cur=sl_next;sl_next=(sl_next==(NSLOT-1)*SLOTB)?0:sl_next+SLOTB;}while(0)
; template<int THRL> __device__ __forceinline__ void attn_unit(int b,int h,int qb,const bf16*Q,const bf16*__restrict__ K,const bf16*__restrict__ V,bf16*O,char*shm){
;     ...
;   _Pragma("unroll") for(int r=0;r<16;++r)pA1[r]=__builtin_amdgcn_exp2f(pA1[r]);
;   WAIT_BAR(0);
;   DMA_K(3,0);DMA_V(1,SLOTB);
;   ROT();
;   kload8(kf,kp0+sl_cur);
;   WAIT_BAR(2);
;   s16x4 vlo[8],vhi[8]; u32x4 pw0,pw1,pw2,pw3;
	v_exp_f32_e32 v48, v0
	v_exp_f32_e32 v49, v1
	v_lshl_add_u64 v[0:1], v[186:187], 0, s[86:87]
	s_mov_b32 m0, s38
	s_nop 0
	global_load_lds_dwordx4 v[0:1], off
	v_lshl_add_u64 v[0:1], v[188:189], 0, s[82:83]
	s_add_i32 s6, s38, 0x8000
	s_mov_b32 m0, s6
	s_nop 0
	global_load_lds_dwordx4 v[0:1], off
	ds_read_b128 v[172:175], v208 offset:8192
	ds_read_b128 v[168:171], v208 offset:8704
	ds_read_b128 v[164:167], v208 offset:10240
	ds_read_b128 v[160:163], v208 offset:10752
	ds_read_b128 v[156:159], v208 offset:12288
	ds_read_b128 v[152:155], v208 offset:12800
	ds_read_b128 v[148:151], v208 offset:14336
	ds_read_b128 v[144:147], v208 offset:14848
	s_add_u32 s44, s42, s44
	s_addc_u32 s45, s43, s45
	s_add_u32 s23, s50, s42
	v_exp_f32_e32 v64, v16
	v_exp_f32_e32 v65, v17
	v_exp_f32_e32 v66, v18
	v_exp_f32_e32 v67, v19
	v_exp_f32_e32 v68, v20
	v_exp_f32_e32 v69, v21
	v_exp_f32_e32 v70, v22
	v_exp_f32_e32 v71, v23
	v_exp_f32_e32 v72, v24
	v_exp_f32_e32 v73, v25
	v_exp_f32_e32 v74, v26
	v_exp_f32_e32 v75, v27
	v_exp_f32_e32 v76, v28
	v_exp_f32_e32 v77, v29
	v_exp_f32_e32 v78, v30
	v_exp_f32_e32 v79, v31
	v_exp_f32_e32 v50, v2
	v_exp_f32_e32 v51, v3
	v_exp_f32_e32 v52, v4
	v_exp_f32_e32 v53, v5
	v_exp_f32_e32 v54, v6
	v_exp_f32_e32 v55, v7
	v_exp_f32_e32 v56, v8
	v_exp_f32_e32 v57, v9
	v_exp_f32_e32 v58, v10
	v_exp_f32_e32 v59, v11
	v_exp_f32_e32 v60, v12
	v_exp_f32_e32 v61, v13
	v_exp_f32_e32 v62, v14
	v_exp_f32_e32 v63, v15
	v_and_b32_e32 v0, 3, v82
	s_addc_u32 s42, s51, s43
	s_waitcnt vmcnt(2) lgkmcnt(0)
	s_barrier
	v_lshl_or_b32 v0, v0, 4, s23
	v_mov_b32_e32 v1, s42
	v_lshl_add_u64 v[190:191], s[44:45], 0, v[180:181]
	v_lshl_add_u64 v[0:1], v[0:1], 0, v[80:81]
	v_mov_b32_e32 v180, 0
	v_cmp_gt_u32_e64 s[6:7], 32, v196
	v_lshl_add_u64 v[192:193], s[10:11], 0, v[190:191]
	v_lshl_add_u64 v[194:195], s[14:15], 0, v[0:1]
	v_mov_b32_e32 v0, 0
	v_mov_b32_e32 v1, v180
	v_mov_b32_e32 v2, v180
	v_mov_b32_e32 v3, v180
	v_mov_b32_e32 v4, v180
	v_mov_b32_e32 v5, v180
	v_mov_b32_e32 v6, v180
	v_mov_b32_e32 v7, v180
	v_mov_b32_e32 v8, v180
	v_mov_b32_e32 v9, v180
	v_mov_b32_e32 v10, v180
	v_mov_b32_e32 v11, v180
	v_mov_b32_e32 v12, v180
	v_mov_b32_e32 v13, v180
	v_mov_b32_e32 v14, v180
	v_mov_b32_e32 v15, v180
	v_mov_b32_e32 v16, 0
	v_mov_b32_e32 v17, v180
	v_mov_b32_e32 v18, v180
	v_mov_b32_e32 v19, v180
	v_mov_b32_e32 v20, v180
	v_mov_b32_e32 v21, v180
	v_mov_b32_e32 v22, v180
	v_mov_b32_e32 v23, v180
	v_mov_b32_e32 v24, v180
	v_mov_b32_e32 v25, v180
	v_mov_b32_e32 v26, v180
	v_mov_b32_e32 v27, v180
	v_mov_b32_e32 v28, v180
	v_mov_b32_e32 v29, v180
	v_mov_b32_e32 v30, v180
	v_mov_b32_e32 v31, v180
.LBB0_778:
	v_add_u32_e32 v214, s22, v209
	ds_read_b64_tr_b16 v[176:177], v214 offset:24576
	ds_read_b64_tr_b16 v[178:179], v214 offset:25088
	s_waitcnt lgkmcnt(9)
	v_mfma_f32_32x32x16_bf16 v[96:111], v[172:175], v[140:143], v[32:47]
	v_add_f32_e32 v80, v64, v65
	v_add_f32_e32 v80, v66, v80
	v_add_f32_e32 v80, v67, v80
	v_add_f32_e32 v80, v68, v80
	v_add_f32_e32 v80, v69, v80
	v_cvt_pk_bf16_f32 v132, v64, v65
	v_cvt_pk_bf16_f32 v133, v66, v67
	ds_read_b64_tr_b16 v[172:173], v214 offset:28672
	ds_read_b64_tr_b16 v[174:175], v214 offset:29184
	v_add_f32_e32 v64, v70, v80
	s_waitcnt lgkmcnt(10)
	v_mfma_f32_32x32x16_bf16 v[80:95], v[168:171], v[140:143], v[32:47]
	v_add_f32_e32 v64, v71, v64
	v_add_f32_e32 v64, v72, v64
	v_add_f32_e32 v112, v73, v64
	v_cvt_pk_bf16_f32 v134, v68, v69
	v_cvt_pk_bf16_f32 v135, v70, v71
	ds_read_b64_tr_b16 v[64:65], v214 offset:25600
	ds_read_b64_tr_b16 v[66:67], v214 offset:26112
	s_waitcnt lgkmcnt(11)
	v_mfma_f32_32x32x16_bf16 v[96:111], v[164:167], v[136:139], v[96:111]
	v_add_f32_e32 v68, v74, v112
	v_add_f32_e32 v68, v75, v68
	v_add_f32_e32 v68, v76, v68
	v_add_f32_e32 v112, v77, v68
	v_cvt_pk_bf16_f32 v124, v72, v73
	v_cvt_pk_bf16_f32 v125, v74, v75
	ds_read_b64_tr_b16 v[68:69], v214 offset:29696
	ds_read_b64_tr_b16 v[70:71], v214 offset:30208
	s_waitcnt lgkmcnt(12)
	v_mfma_f32_32x32x16_bf16 v[80:95], v[160:163], v[136:139], v[80:95]
	v_add_f32_e32 v72, v78, v112
	v_add_f32_e32 v72, v79, v72
	v_add_f32_e32 v72, v48, v72
	v_add_f32_e32 v112, v49, v72
	v_cvt_pk_bf16_f32 v126, v76, v77
	v_cvt_pk_bf16_f32 v127, v78, v79
	ds_read_b64_tr_b16 v[72:73], v214 offset:26624
	ds_read_b64_tr_b16 v[74:75], v214 offset:27136
	s_waitcnt lgkmcnt(13)
	v_mfma_f32_32x32x16_bf16 v[96:111], v[156:159], v[128:131], v[96:111]
	v_add_f32_e32 v76, v50, v112
	v_add_f32_e32 v76, v51, v76
	v_add_f32_e32 v76, v52, v76
	v_add_f32_e32 v76, v53, v76
	v_cvt_pk_bf16_f32 v116, v48, v49
	v_cvt_pk_bf16_f32 v117, v50, v51
	ds_read_b64_tr_b16 v[48:49], v214 offset:30720
	ds_read_b64_tr_b16 v[50:51], v214 offset:31232
	s_waitcnt lgkmcnt(14)
	v_mfma_f32_32x32x16_bf16 v[80:95], v[152:155], v[128:131], v[80:95]
	v_add_f32_e32 v76, v54, v76
	v_add_f32_e32 v76, v55, v76
	v_add_f32_e32 v76, v56, v76
	v_add_f32_e32 v76, v57, v76
	v_cvt_pk_bf16_f32 v118, v52, v53
	v_cvt_pk_bf16_f32 v119, v54, v55
	ds_read_b64_tr_b16 v[52:53], v214 offset:27648
	ds_read_b64_tr_b16 v[54:55], v214 offset:28160
	s_waitcnt lgkmcnt(14)
	v_mfma_f32_32x32x16_bf16 v[96:111], v[148:151], v[120:123], v[96:111]
	v_add_f32_e32 v76, v58, v76
	v_add_f32_e32 v76, v59, v76
	v_add_f32_e32 v76, v60, v76
	v_add_f32_e32 v76, v61, v76
	v_cvt_pk_bf16_f32 v112, v56, v57
	v_cvt_pk_bf16_f32 v113, v58, v59
	ds_read_b64_tr_b16 v[56:57], v214 offset:31744
	ds_read_b64_tr_b16 v[58:59], v214 offset:32256
	v_mfma_f32_32x32x16_bf16 v[80:95], v[144:147], v[120:123], v[80:95]
	v_add_f32_e32 v76, v62, v76
	v_add_f32_e32 v76, v63, v76
	v_add_f32_e32 v76, 0, v76
	v_cvt_pk_bf16_f32 v114, v60, v61
	v_cvt_pk_bf16_f32 v115, v62, v63
	v_lshl_add_u64 v[60:61], v[192:193], 0, s[86:87]
	s_add_i32 s22, s3, s38
	s_mov_b32 m0, s22
	s_nop 0
	global_load_lds_dwordx4 v[60:61], off
	v_lshl_add_u64 v[60:61], v[194:195], 0, s[82:83]
	s_add_i32 s22, s53, s39
	s_mov_b32 m0, s22
	s_nop 0
	global_load_lds_dwordx4 v[60:61], off
	v_max_f32_e32 v60, v96, v97
	v_max3_f32 v61, v98, v99, v81
	v_max3_f32 v60, v60, v80, v82
	v_max3_f32 v60, v60, v83, v100
	v_max3_f32 v61, v61, v102, v103
	v_max3_f32 v60, v60, v101, v84
	v_max3_f32 v61, v61, v86, v87
	v_max3_f32 v60, v60, v85, v104
	v_max3_f32 v61, v61, v106, v107
	v_max3_f32 v60, v60, v105, v88
	v_max3_f32 v61, v61, v90, v91
	v_max3_f32 v60, v60, v89, v108
	v_max3_f32 v61, v61, v110, v111
	v_max3_f32 v60, v60, v109, v92
	v_max3_f32 v61, v61, v94, v95
	v_max3_f32 v60, v60, v93, v61
	v_mov_b32_e32 v61, v60
	s_nop 1
	v_permlane32_swap_b32_e32 v60, v61
	v_max_f32_e32 v60, v60, v61
	v_cmp_lt_f32_e32 vcc, s12, v60
	s_cmp_lg_u64 vcc, 0
	v_add_f32_e32 v180, v180, v76
	s_cselect_b64 s[42:43], -1, 0
	s_cbranch_vccnz .LBB0_786

.LBB0_781:
	s_add_i32 s22, s53, 0x2000
	s_cmpk_lg_i32 s53, 0x4000
	s_cselect_b32 s44, s22, 0
	v_add_u32_e32 v214, s3, v209
	ds_read_b64_tr_b16 v[148:149], v214 offset:24576
	ds_read_b64_tr_b16 v[150:151], v214 offset:25088
	s_waitcnt lgkmcnt(9)
	v_mfma_f32_32x32x16_bf16 v[64:79], v[60:63], v[140:143], v[32:47]
	v_add_f32_e32 v48, v96, v97
	v_add_f32_e32 v48, v98, v48
	v_add_f32_e32 v48, v99, v48
	v_add_f32_e32 v48, v100, v48
	v_add_f32_e32 v48, v101, v48
	v_cvt_pk_bf16_f32 v132, v96, v97
	v_cvt_pk_bf16_f32 v133, v98, v99
	ds_read_b64_tr_b16 v[144:145], v214 offset:28672
	ds_read_b64_tr_b16 v[146:147], v214 offset:29184
	v_add_f32_e32 v48, v102, v48
	v_add_f32_e32 v48, v103, v48
	v_add_f32_e32 v48, v104, v48
	v_add_f32_e32 v112, v105, v48
	s_waitcnt lgkmcnt(10)
	v_mfma_f32_32x32x16_bf16 v[48:63], v[172:175], v[140:143], v[32:47]
	v_cvt_pk_bf16_f32 v134, v100, v101
	v_cvt_pk_bf16_f32 v135, v102, v103
	ds_read_b64_tr_b16 v[96:97], v214 offset:25600
	ds_read_b64_tr_b16 v[98:99], v214 offset:26112
	s_waitcnt lgkmcnt(11)
	v_mfma_f32_32x32x16_bf16 v[64:79], v[176:179], v[136:139], v[64:79]
	v_add_f32_e32 v100, v106, v112
	v_add_f32_e32 v100, v107, v100
	v_add_f32_e32 v100, v108, v100
	v_add_f32_e32 v112, v109, v100
	v_cvt_pk_bf16_f32 v124, v104, v105
	v_cvt_pk_bf16_f32 v125, v106, v107
	ds_read_b64_tr_b16 v[100:101], v214 offset:29696
	ds_read_b64_tr_b16 v[102:103], v214 offset:30208
	s_waitcnt lgkmcnt(12)
	v_mfma_f32_32x32x16_bf16 v[48:63], v[168:171], v[136:139], v[48:63]
	v_add_f32_e32 v104, v110, v112
	v_add_f32_e32 v104, v111, v104
	v_add_f32_e32 v104, v80, v104
	v_add_f32_e32 v112, v81, v104
	v_cvt_pk_bf16_f32 v126, v108, v109
	v_cvt_pk_bf16_f32 v127, v110, v111
	ds_read_b64_tr_b16 v[104:105], v214 offset:26624
	ds_read_b64_tr_b16 v[106:107], v214 offset:27136
	s_waitcnt lgkmcnt(13)
	v_mfma_f32_32x32x16_bf16 v[64:79], v[164:167], v[128:131], v[64:79]
	v_add_f32_e32 v108, v82, v112
	v_add_f32_e32 v108, v83, v108
	v_add_f32_e32 v108, v84, v108
	v_add_f32_e32 v108, v85, v108
	v_cvt_pk_bf16_f32 v116, v80, v81
	v_cvt_pk_bf16_f32 v117, v82, v83
	ds_read_b64_tr_b16 v[80:81], v214 offset:30720
	ds_read_b64_tr_b16 v[82:83], v214 offset:31232
	s_waitcnt lgkmcnt(14)
	v_mfma_f32_32x32x16_bf16 v[48:63], v[160:163], v[128:131], v[48:63]
	v_add_f32_e32 v108, v86, v108
	v_add_f32_e32 v108, v87, v108
	v_add_f32_e32 v108, v88, v108
	v_add_f32_e32 v108, v89, v108
	v_cvt_pk_bf16_f32 v118, v84, v85
	v_cvt_pk_bf16_f32 v119, v86, v87
	ds_read_b64_tr_b16 v[84:85], v214 offset:27648
	ds_read_b64_tr_b16 v[86:87], v214 offset:28160
	s_waitcnt lgkmcnt(14)
	v_mfma_f32_32x32x16_bf16 v[64:79], v[156:159], v[120:123], v[64:79]
	v_add_f32_e32 v108, v90, v108
	v_add_f32_e32 v108, v91, v108
	v_add_f32_e32 v108, v92, v108
	v_add_f32_e32 v108, v93, v108
	v_cvt_pk_bf16_f32 v112, v88, v89
	v_cvt_pk_bf16_f32 v113, v90, v91
	ds_read_b64_tr_b16 v[88:89], v214 offset:31744
	ds_read_b64_tr_b16 v[90:91], v214 offset:32256
	v_mfma_f32_32x32x16_bf16 v[48:63], v[152:155], v[120:123], v[48:63]
	v_add_f32_e32 v108, v94, v108
	v_add_f32_e32 v108, v95, v108
	v_add_f32_e32 v108, 0, v108
	v_cvt_pk_bf16_f32 v114, v92, v93
	v_cvt_pk_bf16_f32 v115, v94, v95
	v_lshl_add_u64 v[92:93], v[192:193], 0, s[88:89]
	s_add_i32 s3, s53, s38
	s_mov_b32 m0, s3
	s_nop 0
	global_load_lds_dwordx4 v[92:93], off
	v_max_f32_e32 v92, v64, v65
	s_nop 1
	v_max3_f32 v93, v66, v67, v49
	v_max3_f32 v92, v92, v48, v50
	v_max3_f32 v92, v92, v51, v68
	v_max3_f32 v93, v93, v70, v71
	v_max3_f32 v92, v92, v69, v52
	v_max3_f32 v93, v93, v54, v55
	v_max3_f32 v92, v92, v53, v72
	v_max3_f32 v93, v93, v74, v75
	v_max3_f32 v92, v92, v73, v56
	v_max3_f32 v93, v93, v58, v59
	v_max3_f32 v92, v92, v57, v76
	v_max3_f32 v93, v93, v78, v79
	v_max3_f32 v92, v92, v77, v60
	v_max3_f32 v93, v93, v62, v63
	v_max3_f32 v92, v92, v61, v93
	v_mov_b32_e32 v93, v92
	s_nop 1
	v_permlane32_swap_b32_e32 v92, v93
	v_max_f32_e32 v92, v92, v93
	v_lshl_add_u64 v[194:195], v[194:195], 0, s[84:85]
	s_add_i32 s3, s44, s39
	s_mov_b32 m0, s3
	s_nop 0
	global_load_lds_dwordx4 v[194:195], off
	v_cmp_lt_f32_e32 vcc, s12, v92
	s_cmp_lg_u64 vcc, 0
	v_add_f32_e32 v180, v180, v108
	s_cselect_b64 s[42:43], -1, 0
	s_cbranch_vccnz .LBB0_789

; __device__ __forceinline__ void glds16(const void*gsrc,unsigned lds_dst){unsigned keep;
;   asm volatile("s_mov_b32 %0, m0\n\ts_mov_b32 m0, %2\n\ts_nop 0\n\tglobal_load_lds_dwordx4 %1, off\n\ts_mov_b32 m0, %0":"=&s"(keep):"v"(gsrc),"s"(lds_dst):"memory");}
.LBB0_793:
	v_add_u32_e32 v192, s22, v209
	ds_read_b64_tr_b16 v[176:177], v192 offset:24576
	ds_read_b64_tr_b16 v[178:179], v192 offset:25088
	s_waitcnt lgkmcnt(9)
	v_mfma_f32_32x32x16_bf16 v[96:111], v[172:175], v[140:143], v[32:47]
	v_add_f32_e32 v80, v64, v65
	v_add_f32_e32 v80, v66, v80
	v_add_f32_e32 v80, v67, v80
	v_add_f32_e32 v80, v68, v80
	v_add_f32_e32 v80, v69, v80
	v_cvt_pk_bf16_f32 v132, v64, v65
	v_cvt_pk_bf16_f32 v133, v66, v67
	ds_read_b64_tr_b16 v[172:173], v192 offset:28672
	ds_read_b64_tr_b16 v[174:175], v192 offset:29184
	v_add_f32_e32 v64, v70, v80
	s_waitcnt lgkmcnt(10)
	v_mfma_f32_32x32x16_bf16 v[80:95], v[168:171], v[140:143], v[32:47]
	v_add_f32_e32 v64, v71, v64
	v_add_f32_e32 v64, v72, v64
	v_add_f32_e32 v112, v73, v64
	v_cvt_pk_bf16_f32 v134, v68, v69
	v_cvt_pk_bf16_f32 v135, v70, v71
	ds_read_b64_tr_b16 v[64:65], v192 offset:25600
	ds_read_b64_tr_b16 v[66:67], v192 offset:26112
	s_waitcnt lgkmcnt(11)
	v_mfma_f32_32x32x16_bf16 v[96:111], v[164:167], v[136:139], v[96:111]
	v_add_f32_e32 v68, v74, v112
	v_add_f32_e32 v68, v75, v68
	v_add_f32_e32 v68, v76, v68
	v_add_f32_e32 v112, v77, v68
	v_cvt_pk_bf16_f32 v124, v72, v73
	v_cvt_pk_bf16_f32 v125, v74, v75
	ds_read_b64_tr_b16 v[68:69], v192 offset:29696
	ds_read_b64_tr_b16 v[70:71], v192 offset:30208
	s_waitcnt lgkmcnt(12)
	v_mfma_f32_32x32x16_bf16 v[80:95], v[160:163], v[136:139], v[80:95]
	v_add_f32_e32 v72, v78, v112
	v_add_f32_e32 v72, v79, v72
	v_add_f32_e32 v72, v48, v72
	v_add_f32_e32 v112, v49, v72
	v_cvt_pk_bf16_f32 v126, v76, v77
	v_cvt_pk_bf16_f32 v127, v78, v79
	ds_read_b64_tr_b16 v[72:73], v192 offset:26624
	ds_read_b64_tr_b16 v[74:75], v192 offset:27136
	s_waitcnt lgkmcnt(13)
	v_mfma_f32_32x32x16_bf16 v[96:111], v[156:159], v[128:131], v[96:111]
	v_add_f32_e32 v76, v50, v112
	v_add_f32_e32 v76, v51, v76
	v_add_f32_e32 v76, v52, v76
	v_add_f32_e32 v76, v53, v76
	v_cvt_pk_bf16_f32 v116, v48, v49
	v_cvt_pk_bf16_f32 v117, v50, v51
	ds_read_b64_tr_b16 v[48:49], v192 offset:30720
	ds_read_b64_tr_b16 v[50:51], v192 offset:31232
	s_waitcnt lgkmcnt(14)
	v_mfma_f32_32x32x16_bf16 v[80:95], v[152:155], v[128:131], v[80:95]
	v_add_f32_e32 v76, v54, v76
	v_add_f32_e32 v76, v55, v76
	v_add_f32_e32 v76, v56, v76
	v_add_f32_e32 v76, v57, v76
	v_cvt_pk_bf16_f32 v118, v52, v53
	v_cvt_pk_bf16_f32 v119, v54, v55
	ds_read_b64_tr_b16 v[52:53], v192 offset:27648
	ds_read_b64_tr_b16 v[54:55], v192 offset:28160
	s_waitcnt lgkmcnt(14)
	v_mfma_f32_32x32x16_bf16 v[96:111], v[148:151], v[120:123], v[96:111]
	v_add_f32_e32 v76, v58, v76
	v_add_f32_e32 v76, v59, v76
	v_add_f32_e32 v76, v60, v76
	v_add_f32_e32 v76, v61, v76
	v_cvt_pk_bf16_f32 v112, v56, v57
	v_cvt_pk_bf16_f32 v113, v58, v59
	ds_read_b64_tr_b16 v[56:57], v192 offset:31744
	ds_read_b64_tr_b16 v[58:59], v192 offset:32256
	v_mfma_f32_32x32x16_bf16 v[80:95], v[144:147], v[120:123], v[80:95]
	v_add_f32_e32 v76, v62, v76
	v_add_f32_e32 v76, v63, v76
	v_add_f32_e32 v76, 0, v76
	v_cvt_pk_bf16_f32 v114, v60, v61
	v_cvt_pk_bf16_f32 v115, v62, v63
	s_cmp_gt_u32 s3, 60
	s_cselect_b64 s[44:45], -1, 0
	s_and_b64 vcc, exec, s[44:45]
	s_mov_b64 s[50:51], s[42:43]
	s_cbranch_vccnz .LBB0_795
	s_add_i32 s22, s62, s38
	v_lshl_add_u64 v[60:61], v[190:191], 0, s[86:87]
	s_mov_b32 m0, s22
	s_nop 0
	global_load_lds_dwordx4 v[60:61], off
	s_mul_i32 s68, s3, 0x18000
	s_mov_b64 s[50:51], s[68:69]
.LBB0_795:
	v_lshl_add_u64 v[192:193], s[50:51], 1, v[188:189]
	v_lshl_add_u64 v[60:61], v[192:193], 0, s[82:83]
	s_add_i32 s22, s73, s39
	s_mov_b32 m0, s22
	s_nop 0
	global_load_lds_dwordx4 v[60:61], off
	v_max_f32_e32 v60, v96, v97
	v_max3_f32 v61, v98, v99, v81
	v_max3_f32 v60, v60, v80, v82
	v_max3_f32 v60, v60, v83, v100
	v_max3_f32 v61, v61, v102, v103
	v_max3_f32 v60, v60, v101, v84
	v_max3_f32 v61, v61, v86, v87
	v_max3_f32 v60, v60, v85, v104
	v_max3_f32 v61, v61, v106, v107
	v_max3_f32 v60, v60, v105, v88
	v_max3_f32 v61, v61, v90, v91
	v_max3_f32 v60, v60, v89, v108
	v_max3_f32 v61, v61, v110, v111
	v_max3_f32 v60, v60, v109, v92
	v_max3_f32 v61, v61, v94, v95
	v_max3_f32 v60, v60, v93, v61
	v_mov_b32_e32 v61, v60
	s_nop 1
	v_permlane32_swap_b32_e32 v60, v61
	v_max_f32_e32 v60, v60, v61
	v_cmp_lt_f32_e32 vcc, s12, v60
	s_cmp_lg_u64 vcc, 0
	v_add_f32_e32 v180, v180, v76
	s_cselect_b64 s[52:53], -1, 0
	s_cbranch_vccnz .LBB0_813

; __device__ __forceinline__ void glds16(const void*gsrc,unsigned lds_dst){unsigned keep;
;   asm volatile("s_mov_b32 %0, m0\n\ts_mov_b32 m0, %2\n\ts_nop 0\n\tglobal_load_lds_dwordx4 %1, off\n\ts_mov_b32 m0, %0":"=&s"(keep):"v"(gsrc),"s"(lds_dst):"memory");}
.LBB0_800:
	v_add_u32_e32 v194, s62, v209
	ds_read_b64_tr_b16 v[148:149], v194 offset:24576
	ds_read_b64_tr_b16 v[150:151], v194 offset:25088
	s_waitcnt lgkmcnt(9)
	v_mfma_f32_32x32x16_bf16 v[64:79], v[60:63], v[140:143], v[32:47]
	v_add_f32_e32 v48, v96, v97
	v_add_f32_e32 v48, v98, v48
	v_add_f32_e32 v48, v99, v48
	v_add_f32_e32 v48, v100, v48
	v_add_f32_e32 v48, v101, v48
	v_cvt_pk_bf16_f32 v132, v96, v97
	v_cvt_pk_bf16_f32 v133, v98, v99
	ds_read_b64_tr_b16 v[144:145], v194 offset:28672
	ds_read_b64_tr_b16 v[146:147], v194 offset:29184
	v_add_f32_e32 v48, v102, v48
	v_add_f32_e32 v48, v103, v48
	v_add_f32_e32 v48, v104, v48
	v_add_f32_e32 v112, v105, v48
	s_waitcnt lgkmcnt(10)
	v_mfma_f32_32x32x16_bf16 v[48:63], v[172:175], v[140:143], v[32:47]
	v_cvt_pk_bf16_f32 v134, v100, v101
	v_cvt_pk_bf16_f32 v135, v102, v103
	ds_read_b64_tr_b16 v[96:97], v194 offset:25600
	ds_read_b64_tr_b16 v[98:99], v194 offset:26112
	s_waitcnt lgkmcnt(11)
	v_mfma_f32_32x32x16_bf16 v[64:79], v[176:179], v[136:139], v[64:79]
	v_add_f32_e32 v100, v106, v112
	v_add_f32_e32 v100, v107, v100
	v_add_f32_e32 v100, v108, v100
	v_add_f32_e32 v112, v109, v100
	v_cvt_pk_bf16_f32 v124, v104, v105
	v_cvt_pk_bf16_f32 v125, v106, v107
	ds_read_b64_tr_b16 v[100:101], v194 offset:29696
	ds_read_b64_tr_b16 v[102:103], v194 offset:30208
	s_waitcnt lgkmcnt(12)
	v_mfma_f32_32x32x16_bf16 v[48:63], v[168:171], v[136:139], v[48:63]
	v_add_f32_e32 v104, v110, v112
	v_add_f32_e32 v104, v111, v104
	v_add_f32_e32 v104, v80, v104
	v_add_f32_e32 v112, v81, v104
	v_cvt_pk_bf16_f32 v126, v108, v109
	v_cvt_pk_bf16_f32 v127, v110, v111
	ds_read_b64_tr_b16 v[104:105], v194 offset:26624
	ds_read_b64_tr_b16 v[106:107], v194 offset:27136
	s_waitcnt lgkmcnt(13)
	v_mfma_f32_32x32x16_bf16 v[64:79], v[164:167], v[128:131], v[64:79]
	v_add_f32_e32 v108, v82, v112
	v_add_f32_e32 v108, v83, v108
	v_add_f32_e32 v108, v84, v108
	v_add_f32_e32 v108, v85, v108
	v_cvt_pk_bf16_f32 v116, v80, v81
	v_cvt_pk_bf16_f32 v117, v82, v83
	ds_read_b64_tr_b16 v[80:81], v194 offset:30720
	ds_read_b64_tr_b16 v[82:83], v194 offset:31232
	s_waitcnt lgkmcnt(14)
	v_mfma_f32_32x32x16_bf16 v[48:63], v[160:163], v[128:131], v[48:63]
	v_add_f32_e32 v108, v86, v108
	v_add_f32_e32 v108, v87, v108
	v_add_f32_e32 v108, v88, v108
	v_add_f32_e32 v108, v89, v108
	v_cvt_pk_bf16_f32 v118, v84, v85
	v_cvt_pk_bf16_f32 v119, v86, v87
	ds_read_b64_tr_b16 v[84:85], v194 offset:27648
	ds_read_b64_tr_b16 v[86:87], v194 offset:28160
	s_waitcnt lgkmcnt(14)
	v_mfma_f32_32x32x16_bf16 v[64:79], v[156:159], v[120:123], v[64:79]
	v_add_f32_e32 v108, v90, v108
	v_add_f32_e32 v108, v91, v108
	v_add_f32_e32 v108, v92, v108
	v_add_f32_e32 v108, v93, v108
	v_cvt_pk_bf16_f32 v112, v88, v89
	v_cvt_pk_bf16_f32 v113, v90, v91
	ds_read_b64_tr_b16 v[88:89], v194 offset:31744
	ds_read_b64_tr_b16 v[90:91], v194 offset:32256
	v_mfma_f32_32x32x16_bf16 v[48:63], v[152:155], v[120:123], v[48:63]
	v_add_f32_e32 v108, v94, v108
	v_add_f32_e32 v108, v95, v108
	v_add_f32_e32 v108, 0, v108
	v_cvt_pk_bf16_f32 v114, v92, v93
	v_cvt_pk_bf16_f32 v115, v94, v95
	s_cmp_gt_u32 s3, 59
	s_cselect_b64 s[52:53], -1, 0
	s_and_b64 vcc, exec, s[52:53]
	s_cbranch_vccnz .LBB0_802
	v_lshl_add_u64 v[92:93], s[50:51], 1, v[186:187]
	s_add_i32 s22, s73, s38
	v_lshl_add_u64 v[92:93], v[92:93], 0, s[88:89]
	s_mov_b32 m0, s22
	s_nop 0
	global_load_lds_dwordx4 v[92:93], off
.LBB0_802:
	s_add_i32 s22, s73, 0x2000
	s_cmpk_lg_i32 s73, 0x4000
	s_cselect_b32 s62, s22, 0
	v_lshl_add_u64 v[92:93], v[192:193], 0, s[84:85]
	s_add_i32 s22, s62, s39
	s_mov_b32 m0, s22
	s_nop 0
	global_load_lds_dwordx4 v[92:93], off
	v_max_f32_e32 v92, v64, v65
	v_max3_f32 v93, v66, v67, v49
	v_max3_f32 v92, v92, v48, v50
	v_max3_f32 v92, v92, v51, v68
	v_max3_f32 v93, v93, v70, v71
	v_max3_f32 v92, v92, v69, v52
	v_max3_f32 v93, v93, v54, v55
	v_max3_f32 v92, v92, v53, v72
	v_max3_f32 v93, v93, v74, v75
	v_max3_f32 v92, v92, v73, v56
	v_max3_f32 v93, v93, v58, v59
	v_max3_f32 v92, v92, v57, v76
	v_max3_f32 v93, v93, v78, v79
	v_max3_f32 v92, v92, v77, v60
	v_max3_f32 v93, v93, v62, v63
	v_max3_f32 v92, v92, v61, v93
	v_mov_b32_e32 v93, v92
	s_nop 1
	v_permlane32_swap_b32_e32 v92, v93
	v_max_f32_e32 v92, v92, v93
	v_cmp_lt_f32_e32 vcc, s12, v92
	s_cmp_lg_u64 vcc, 0
	v_add_f32_e32 v180, v180, v108
	s_cselect_b64 s[50:51], -1, 0
	s_cbranch_vccnz .LBB0_816
